# out-proj K-loop: the dead trailing re-reads of the single-unit case point at the just-fetched K-tiles 14/15 (cache-hot) so the drain wait before the LN epilogue is short
# speedup vs baseline: 1.0022x; 1.0003x over previous
.LBB0_325:
	s_add_u32 s75, s90, 0x100
	s_addc_u32 s83, s91, 0
	s_ashr_i32 s85, s84, 31
	s_lshl_b64 s[2:3], s[84:85], 19
	s_add_u32 s88, s78, s2
	s_addc_u32 s89, s79, s3
	s_add_u32 s100, s40, 0x700
	s_addc_u32 s101, s41, 0
	s_and_b64 s[2:3], s[38:39], exec
	s_cselect_b32 s85, s89, s101
	s_cselect_b32 s92, s88, s100
	s_ashr_i32 s5, s4, 31
	s_lshl_b64 s[2:3], s[4:5], 19
	s_add_u32 s86, s19, s2
	s_addc_u32 s87, s20, s3
	s_add_u32 s100, s90, 0x700
	s_addc_u32 s101, s91, 0
	s_and_b64 s[2:3], s[38:39], exec
	s_cselect_b32 s5, s87, s101
	s_cselect_b32 s94, s86, s100
	s_add_u32 s2, s40, 0x40080
	s_addc_u32 s3, s41, 0
	v_lshl_add_u64 v[6:7], s[2:3], 0, v[2:3]
	v_lshl_add_u64 v[8:9], s[2:3], 0, v[4:5]
	s_mov_b32 s95, -2
	s_mov_b64 s[90:91], 0
